# gla_pass2: gate-column and norm-gain loads of backward chunks issued at chunk start; k/q row loads use one stepped scalar base
# baseline (speedup 1.0000x reference)
; #define LAS __attribute__((address_space(3)))
; template <bool OUT>
; __device__ __forceinline__ void gla_chunks(const Params& p, int l, const bf16_t* proj, LAS unsigned char* lds, int seg, int h, int dir, f32x4 (&Sacc)[4], float* outbuf, float& alog) {
;     ...
;             for (int it = 0; it < 4; ++it) { f32x4 o = {0.f, 0.f, 0.f, 0.f};
; #pragma unroll
;                 for (int ks = 0; ks < 2; ++ks) { const bf16x8 pf = *(const LAS bf16x8*)(PP + (it * 16 + fr) * GP + 32 * ks + 8 * g); o = __builtin_amdgcn_mfma_f32_16x16x32_bf16(pf, bv[ks], o, 0, 0, 0); }
; #pragma unroll
;                 for (int m = 0; m < 2; ++m) { const LAS bf16_t* qp = QT + (it * 16 + fr) * GP + 32 * m + 4 * g; const u32x2 lo = *(const LAS u32x2*)qp, hi = *(const LAS u32x2*)(qp + 16);
;                     u32x4 qw; qw.x = lo.x; qw.y = lo.y; qw.z = hi.x; qw.w = hi.y; o = __builtin_amdgcn_mfma_f32_16x16x32_bf16(__builtin_bit_cast(bf16x8, qw), bs[m], o, 0, 0, 0); }
; #pragma unroll
;                 for (int r = 0; r < 4; ++r) { const int i = it * 16 + 4 * g + r, t = dir ? t0 + 63 - i : t0 + i; outbuf[(size_t)t * 512 + h * 128 + 16 * wv + fr] = o[r]; } }
;         }
; #pragma unroll
;         for (int dt = 0; dt < 4; ++dt) { const f32x4 eb = *(const LAS f32x4*)(EBL + dt * 16 + 4 * g); f32x4 a = Sacc[dt] * eb;
; #pragma unroll
;             for (int ks = 0; ks < 2; ++ks) { const bf16x8 kf = *(const LAS bf16x8*)(KH + (dt * 16 + fr) * GP + 32 * ks + 8 * g); a = __builtin_amdgcn_mfma_f32_16x16x32_bf16(kf, bv[ks], a, 0, 0, 0); }
;             Sacc[dt] = a; }
.Lp2b_rsdone:
	v_cvt_pk_bf16_f32 v16, v22, v16
	v_cvt_pk_bf16_f32 v17, v17, v18
	s_nop 0
	v_add_u32_e32 v18, v111, v118
	ds_write_b64 v18, v[16:17] offset:46080
	s_waitcnt lgkmcnt(0)
	s_barrier
	ds_read_b128 v[20:23], v135 offset:27648
	ds_read_b128 v[16:19], v135 offset:27712
	ds_read_b128 v[156:159], v136 offset:46080
	ds_read_b128 v[160:163], v136 offset:46144
	ds_read2_b64 v[190:193], v137 offset1:4
	ds_read2_b64 v[194:197], v137 offset0:8 offset1:12
	ds_read_b128 v[164:167], v136 offset:48384
	ds_read_b128 v[168:171], v136 offset:48448
	v_add_u32_e32 v40, 0x800, v137
	ds_read2_b64 v[198:201], v40 offset0:32 offset1:36
	ds_read2_b64 v[202:205], v40 offset0:40 offset1:44
	ds_read_b128 v[172:175], v136 offset:50688
	ds_read_b128 v[176:179], v136 offset:50752
	ds_read_b128 v[180:183], v136 offset:52992
	ds_read_b128 v[184:187], v136 offset:53056
	v_cvt_pk_bf16_f32 v28, v8, v9
	v_cvt_pk_bf16_f32 v29, v10, v11
	v_cvt_pk_bf16_f32 v30, v0, v1
	v_cvt_pk_bf16_f32 v31, v2, v3
	v_cvt_pk_bf16_f32 v24, v4, v5
	v_cvt_pk_bf16_f32 v25, v6, v7
	v_cvt_pk_bf16_f32 v26, v12, v13
	v_cvt_pk_bf16_f32 v27, v14, v15
	s_waitcnt lgkmcnt(11)
	v_mfma_f32_16x16x32_bf16 v[32:35], v[156:159], v[20:23], 0
	s_waitcnt lgkmcnt(10)
	v_mfma_f32_16x16x32_bf16 v[32:35], v[160:163], v[16:19], v[32:35]
	s_waitcnt lgkmcnt(9)
	v_mfma_f32_16x16x32_bf16 v[32:35], v[190:193], v[28:31], v[32:35]
	s_waitcnt lgkmcnt(8)
	v_mfma_f32_16x16x32_bf16 v[32:35], v[194:197], v[24:27], v[32:35]
	v_add_u32_e32 v40, 0x1000, v137
	ds_read2_b64 v[138:141], v40 offset0:64 offset1:68
	ds_read2_b64 v[142:145], v40 offset0:72 offset1:76
	v_add_u32_e32 v40, 0x1800, v137
	ds_read2_b64 v[146:149], v40 offset0:96 offset1:100
	ds_read2_b64 v[150:153], v40 offset0:104 offset1:108
	s_waitcnt lgkmcnt(11)
	v_mfma_f32_16x16x32_bf16 v[36:39], v[164:167], v[20:23], 0
	s_waitcnt lgkmcnt(10)
	v_mfma_f32_16x16x32_bf16 v[36:39], v[168:171], v[16:19], v[36:39]
	s_waitcnt lgkmcnt(9)
	v_mfma_f32_16x16x32_bf16 v[36:39], v[198:201], v[28:31], v[36:39]
	s_waitcnt lgkmcnt(8)
	v_mfma_f32_16x16x32_bf16 v[36:39], v[202:205], v[24:27], v[36:39]
	ds_write_b32 v41, v32
	ds_write_b32 v41, v33 offset:528
	ds_write_b32 v41, v34 offset:1056
	ds_write_b32 v41, v35 offset:1584
	s_waitcnt lgkmcnt(7)
	v_mfma_f32_16x16x32_bf16 v[32:35], v[172:175], v[20:23], 0
	s_waitcnt lgkmcnt(6)
	v_mfma_f32_16x16x32_bf16 v[32:35], v[176:179], v[16:19], v[32:35]
	s_waitcnt lgkmcnt(3)
	v_mfma_f32_16x16x32_bf16 v[32:35], v[138:141], v[28:31], v[32:35]
	s_waitcnt lgkmcnt(2)
	v_mfma_f32_16x16x32_bf16 v[32:35], v[142:145], v[24:27], v[32:35]
	ds_write_b32 v41, v36 offset:8448
	ds_write_b32 v41, v37 offset:8976
	ds_write_b32 v41, v38 offset:9504
	ds_write_b32 v41, v39 offset:10032
	ds_read_b128 v[156:159], v82 offset:55296
	ds_read_b128 v[160:163], v82 offset:55360
	ds_read_b128 v[164:167], v82 offset:55424
	ds_read_b128 v[168:171], v82 offset:55488
	ds_read_b128 v[190:193], v136 offset:18432
	ds_read_b128 v[194:197], v136 offset:18496
	ds_read_b128 v[198:201], v136 offset:20736
	ds_read_b128 v[202:205], v136 offset:20800
	v_mfma_f32_16x16x32_bf16 v[36:39], v[180:183], v[20:23], 0
	v_mfma_f32_16x16x32_bf16 v[36:39], v[184:187], v[16:19], v[36:39]
	s_waitcnt lgkmcnt(9)
	v_mfma_f32_16x16x32_bf16 v[36:39], v[146:149], v[28:31], v[36:39]
	s_waitcnt lgkmcnt(8)
	v_mfma_f32_16x16x32_bf16 v[36:39], v[150:153], v[24:27], v[36:39]
	ds_read_b128 v[172:175], v136 offset:23040
	ds_read_b128 v[176:179], v136 offset:23104
	ds_read_b128 v[180:183], v136 offset:25344
	ds_read_b128 v[184:187], v136 offset:25408
	ds_write_b32 v41, v32 offset:16896
	ds_write_b32 v41, v33 offset:17424
	ds_write_b32 v41, v34 offset:17952
	ds_write_b32 v41, v35 offset:18480
	s_waitcnt lgkmcnt(8)
	v_pk_mul_f32 v[8:9], v[8:9], v[156:157]
	v_pk_mul_f32 v[10:11], v[10:11], v[158:159]
	v_pk_mul_f32 v[0:1], v[0:1], v[160:161]
	v_pk_mul_f32 v[2:3], v[2:3], v[162:163]
	v_pk_mul_f32 v[4:5], v[4:5], v[164:165]
	v_pk_mul_f32 v[6:7], v[6:7], v[166:167]
	v_pk_mul_f32 v[12:13], v[12:13], v[168:169]
	v_pk_mul_f32 v[14:15], v[14:15], v[170:171]
	ds_write_b32 v41, v36 offset:25344
	ds_write_b32 v41, v37 offset:25872
	ds_write_b32 v41, v38 offset:26400
	ds_write_b32 v41, v39 offset:26928
	s_waitcnt lgkmcnt(7)
	v_mfma_f32_16x16x32_bf16 v[8:11], v[190:193], v[20:23], v[8:11]
	s_waitcnt lgkmcnt(6)
	v_mfma_f32_16x16x32_bf16 v[8:11], v[194:197], v[16:19], v[8:11]
	s_waitcnt lgkmcnt(5)
	v_mfma_f32_16x16x32_bf16 v[0:3], v[198:201], v[20:23], v[0:3]
	s_waitcnt lgkmcnt(4)
	v_mfma_f32_16x16x32_bf16 v[0:3], v[202:205], v[16:19], v[0:3]
	s_waitcnt lgkmcnt(3)
	v_mfma_f32_16x16x32_bf16 v[4:7], v[172:175], v[20:23], v[4:7]
	s_waitcnt lgkmcnt(2)
	v_mfma_f32_16x16x32_bf16 v[4:7], v[176:179], v[16:19], v[4:7]
	s_waitcnt lgkmcnt(1)
	v_mfma_f32_16x16x32_bf16 v[12:15], v[180:183], v[20:23], v[12:15]
	s_waitcnt lgkmcnt(0)
	v_mfma_f32_16x16x32_bf16 v[12:15], v[184:187], v[16:19], v[12:15]
	s_add_i32 s51, s51, 1
	s_add_i32 s64, s64, -1
	s_cmp_lg_u32 s51, 4
	s_waitcnt lgkmcnt(0)
	s_barrier
; __device__ void gla_pass2(const Params& p, int l, const bf16_t* proj, bf16_t* ycat, LAS unsigned char* lds) {
;     ...
;         const f32x2 gg = *(const f32x2*)(p.gng + l * 512 + h * 128 + lane * 2);
;         for (int j0 = 0; j0 < 32; j0 += 8) {
;             f32x2 of[8], ob[8]; unsigned rw[8];
; #pragma unroll
;             for (int j = 0; j < 8; ++j) { const int t = seg * SEGLEN + wv * 32 + j0 + j; const size_t oo = (size_t)t * 512 + h * 128 + lane * 2;
;                 of[j] = *(const f32x2*)(OF + oo); ob[j] = *(const f32x2*)(OB + oo); rw[j] = *(const unsigned*)(proj + (size_t)t * NP + GR + h * 128 + lane * 2); }
; #pragma unroll
;             for (int j = 0; j < 8; ++j) { const int t = seg * SEGLEN + wv * 32 + j0 + j;
;                 const float o0 = of[j][0] + ob[j][0], o1 = of[j][1] + ob[j][1];
;                 const float ss = wave_sum(o0 * o0 + o1 * o1);
;                 const float rs = rsqrtf(ss * (1.0f / 128.0f) + 1e-6f);
	v_and_b32_e32 v166, 63, v83
	s_lshl_b32 s40, s66, 2
	v_lshlrev_b32_e32 v167, 2, v166
	v_add_u32_e32 v167, s40, v167
	v_lshl_add_u32 v168, v90, 13, v167
	v_lshlrev_b32_e32 v169, 3, v90
	v_sub_u32_e32 v170, 56, v169
	v_mul_u32_u24_e32 v170, 0x210, v170
	v_lshl_add_u32 v170, v166, 3, v170
	v_add_u32_e32 v170, 0xe400, v170
	v_mul_u32_u24_e32 v171, 0x210, v169
	v_lshl_add_u32 v171, v166, 3, v171
	v_add_u32_e32 v171, 0x16800, v171
	ds_read_b64 v[138:139], v170 offset:3696
	ds_read_b64 v[140:141], v170 offset:3168
	ds_read_b64 v[142:143], v170 offset:2640
	ds_read_b64 v[144:145], v170 offset:2112
	ds_read_b64 v[146:147], v170 offset:1584
	ds_read_b64 v[148:149], v170 offset:1056
	ds_read_b64 v[150:151], v170 offset:528
	ds_read_b64 v[152:153], v170 offset:0
	ds_read_b64 v[16:17], v171
	ds_read_b64 v[18:19], v171 offset:528
	ds_read_b64 v[20:21], v171 offset:1056
	ds_read_b64 v[22:23], v171 offset:1584
	ds_read_b64 v[24:25], v171 offset:2112
	ds_read_b64 v[26:27], v171 offset:2640
	ds_read_b64 v[28:29], v171 offset:3168
	ds_read_b64 v[30:31], v171 offset:3696
	s_lshl_b32 s54, s52, 10
	s_add_u32 s54, s54, 0x30601000
	s_add_u32 s54, s86, s54
	s_addc_u32 s55, s87, 0
	s_add_u32 s56, s54, 0x1000
	s_addc_u32 s57, s55, 0
	s_waitcnt lgkmcnt(0)
	v_add_f32_e32 v16, v16, v138
	v_add_f32_e32 v17, v17, v139
	v_mul_f32_e32 v138, v16, v16
	v_mul_f32_e32 v139, v17, v17
	v_add_f32_e32 v138, v138, v139
	v_add_f32_e32 v18, v18, v140
	v_add_f32_e32 v19, v19, v141
	v_mul_f32_e32 v140, v18, v18
	v_mul_f32_e32 v141, v19, v19
	v_add_f32_e32 v140, v140, v141
	v_add_f32_e32 v20, v20, v142
	v_add_f32_e32 v21, v21, v143
	v_mul_f32_e32 v142, v20, v20
	v_mul_f32_e32 v143, v21, v21
	v_add_f32_e32 v142, v142, v143
	v_add_f32_e32 v22, v22, v144
	v_add_f32_e32 v23, v23, v145
	v_mul_f32_e32 v144, v22, v22
	v_mul_f32_e32 v145, v23, v23
	v_add_f32_e32 v144, v144, v145
	v_add_f32_e32 v24, v24, v146
	v_add_f32_e32 v25, v25, v147
	v_mul_f32_e32 v146, v24, v24
	v_mul_f32_e32 v147, v25, v25
	v_add_f32_e32 v146, v146, v147
	v_add_f32_e32 v26, v26, v148
	v_add_f32_e32 v27, v27, v149
	v_mul_f32_e32 v148, v26, v26
	v_mul_f32_e32 v149, v27, v27
	v_add_f32_e32 v148, v148, v149
	v_add_f32_e32 v28, v28, v150
	v_add_f32_e32 v29, v29, v151
	v_mul_f32_e32 v150, v28, v28
	v_mul_f32_e32 v151, v29, v29
	v_add_f32_e32 v150, v150, v151
	v_add_f32_e32 v30, v30, v152
	v_add_f32_e32 v31, v31, v153
	v_mul_f32_e32 v152, v30, v30
	v_mul_f32_e32 v153, v31, v31
	v_add_f32_e32 v152, v152, v153
	v_mov_b32_e32 v139, v138
	v_mov_b32_e32 v141, v140
	v_mov_b32_e32 v143, v142
	v_mov_b32_e32 v145, v144
	v_mov_b32_e32 v147, v146
	v_mov_b32_e32 v149, v148
	v_mov_b32_e32 v151, v150
	v_mov_b32_e32 v153, v152
	v_permlane32_swap_b32_e32 v139, v138
	v_permlane32_swap_b32_e32 v141, v140
	v_permlane32_swap_b32_e32 v143, v142
	v_permlane32_swap_b32_e32 v145, v144
	v_permlane32_swap_b32_e32 v147, v146
	v_permlane32_swap_b32_e32 v149, v148
	v_permlane32_swap_b32_e32 v151, v150
	v_permlane32_swap_b32_e32 v153, v152
	v_add_f32_e32 v138, v138, v139
	v_add_f32_e32 v140, v140, v141
	v_add_f32_e32 v142, v142, v143
	v_add_f32_e32 v144, v144, v145
	v_add_f32_e32 v146, v146, v147
	v_add_f32_e32 v148, v148, v149
	v_add_f32_e32 v150, v150, v151
	v_add_f32_e32 v152, v152, v153
	v_mov_b32_e32 v139, v138
	v_mov_b32_e32 v141, v140
	v_mov_b32_e32 v143, v142
	v_mov_b32_e32 v145, v144
	v_mov_b32_e32 v147, v146
	v_mov_b32_e32 v149, v148
	v_mov_b32_e32 v151, v150
	v_mov_b32_e32 v153, v152
	v_permlane16_swap_b32_e32 v139, v138
	v_permlane16_swap_b32_e32 v141, v140
	v_permlane16_swap_b32_e32 v143, v142
	v_permlane16_swap_b32_e32 v145, v144
	v_permlane16_swap_b32_e32 v147, v146
	v_permlane16_swap_b32_e32 v149, v148
	v_permlane16_swap_b32_e32 v151, v150
	v_permlane16_swap_b32_e32 v153, v152
	v_add_f32_e32 v138, v138, v139
	v_add_f32_e32 v140, v140, v141
	v_add_f32_e32 v142, v142, v143
	v_add_f32_e32 v144, v144, v145
	v_add_f32_e32 v146, v146, v147
	v_add_f32_e32 v148, v148, v149
	v_add_f32_e32 v150, v150, v151
	v_add_f32_e32 v152, v152, v153
	v_add_f32_dpp v138, v138, v138 row_ror:8 row_mask:0xf bank_mask:0xf
	v_add_f32_dpp v140, v140, v140 row_ror:8 row_mask:0xf bank_mask:0xf
	v_add_f32_dpp v142, v142, v142 row_ror:8 row_mask:0xf bank_mask:0xf
	v_add_f32_dpp v144, v144, v144 row_ror:8 row_mask:0xf bank_mask:0xf
	v_add_f32_dpp v146, v146, v146 row_ror:8 row_mask:0xf bank_mask:0xf
	v_add_f32_dpp v148, v148, v148 row_ror:8 row_mask:0xf bank_mask:0xf
	v_add_f32_dpp v150, v150, v150 row_ror:8 row_mask:0xf bank_mask:0xf
	v_add_f32_dpp v152, v152, v152 row_ror:8 row_mask:0xf bank_mask:0xf
	v_add_f32_dpp v138, v138, v138 row_ror:4 row_mask:0xf bank_mask:0xf
	v_add_f32_dpp v140, v140, v140 row_ror:4 row_mask:0xf bank_mask:0xf
	v_add_f32_dpp v142, v142, v142 row_ror:4 row_mask:0xf bank_mask:0xf
	v_add_f32_dpp v144, v144, v144 row_ror:4 row_mask:0xf bank_mask:0xf
	v_add_f32_dpp v146, v146, v146 row_ror:4 row_mask:0xf bank_mask:0xf
	v_add_f32_dpp v148, v148, v148 row_ror:4 row_mask:0xf bank_mask:0xf
	v_add_f32_dpp v150, v150, v150 row_ror:4 row_mask:0xf bank_mask:0xf
	v_add_f32_dpp v152, v152, v152 row_ror:4 row_mask:0xf bank_mask:0xf
	v_add_f32_dpp v138, v138, v138 quad_perm:[2,3,0,1] row_mask:0xf bank_mask:0xf
	v_add_f32_dpp v140, v140, v140 quad_perm:[2,3,0,1] row_mask:0xf bank_mask:0xf
	v_add_f32_dpp v142, v142, v142 quad_perm:[2,3,0,1] row_mask:0xf bank_mask:0xf
	v_add_f32_dpp v144, v144, v144 quad_perm:[2,3,0,1] row_mask:0xf bank_mask:0xf
	v_add_f32_dpp v146, v146, v146 quad_perm:[2,3,0,1] row_mask:0xf bank_mask:0xf
	v_add_f32_dpp v148, v148, v148 quad_perm:[2,3,0,1] row_mask:0xf bank_mask:0xf
	v_add_f32_dpp v150, v150, v150 quad_perm:[2,3,0,1] row_mask:0xf bank_mask:0xf
	v_add_f32_dpp v152, v152, v152 quad_perm:[2,3,0,1] row_mask:0xf bank_mask:0xf
	v_add_f32_dpp v138, v138, v138 quad_perm:[1,0,3,2] row_mask:0xf bank_mask:0xf
	v_add_f32_dpp v140, v140, v140 quad_perm:[1,0,3,2] row_mask:0xf bank_mask:0xf
	v_add_f32_dpp v142, v142, v142 quad_perm:[1,0,3,2] row_mask:0xf bank_mask:0xf
	v_add_f32_dpp v144, v144, v144 quad_perm:[1,0,3,2] row_mask:0xf bank_mask:0xf
	v_add_f32_dpp v146, v146, v146 quad_perm:[1,0,3,2] row_mask:0xf bank_mask:0xf
	v_add_f32_dpp v148, v148, v148 quad_perm:[1,0,3,2] row_mask:0xf bank_mask:0xf
	v_add_f32_dpp v150, v150, v150 quad_perm:[1,0,3,2] row_mask:0xf bank_mask:0xf
	v_add_f32_dpp v152, v152, v152 quad_perm:[1,0,3,2] row_mask:0xf bank_mask:0xf
	s_waitcnt vmcnt(0)
; __device__ __forceinline__ unsigned cvt_pk_bf16(float lo, float hi) { unsigned r; asm("v_cvt_pk_bf16_f32 %0, %1, %2" : "=v"(r) : "v"(lo), "v"(hi)); return r; }
; __device__ __forceinline__ float bf_lo(unsigned w) { return __uint_as_float(w << 16); }
; __device__ __forceinline__ float bf_hi(unsigned w) { return __uint_as_float(w & 0xffff0000u); }
; __device__ void gla_pass2(const Params& p, int l, const bf16_t* proj, bf16_t* ycat, LAS unsigned char* lds) {
;     ...
;             for (int j = 0; j < 8; ++j) { const int t = seg * SEGLEN + wv * 32 + j0 + j;
;                 const float o0 = of[j][0] + ob[j][0], o1 = of[j][1] + ob[j][1];
;                 const float ss = wave_sum(o0 * o0 + o1 * o1);
;                 const float rs = rsqrtf(ss * (1.0f / 128.0f) + 1e-6f);
;                 const float r0 = bf_lo(rw[j]), r1 = bf_hi(rw[j]);
;                 const float y0 = o0 * rs * gg[0] * (r0 / (1.0f + __expf(-r0))), y1 = o1 * rs * gg[1] * (r1 / (1.0f + __expf(-r1)));
;                 *(unsigned*)(ycat + (size_t)2 * SEQ * 512 + (size_t)t * 512 + h * 128 + lane * 2) = cvt_pk_bf16(y0, y1); } }
	v_fmamk_f32 v138, v138, 0x3c000000, v212
	v_cmp_gt_f32_e32 vcc, s1, v138
	v_mul_f32_e32 v174, 0x4b800000, v138
	v_lshlrev_b32_e32 v175, 16, v242
	v_cndmask_b32_e32 v138, v138, v174, vcc
	v_rsq_f32_e32 v138, v138
	v_and_b32_e32 v176, 0xffff0000, v242
	v_mul_f32_e32 v174, 0x45800000, v138
	v_mul_f32_e32 v177, 0xbfb8aa3b, v175
	v_cndmask_b32_e32 v138, v138, v174, vcc
	v_exp_f32_e32 v177, v177
	v_mul_f32_e32 v178, 0xbfb8aa3b, v176
	v_exp_f32_e32 v178, v178
	v_mul_f32_e32 v16, v16, v138
	v_mul_f32_e32 v17, v17, v138
	v_add_f32_e32 v177, 1.0, v177
	v_add_f32_e32 v178, 1.0, v178
	v_mul_f32_e32 v16, v240, v16
	v_mul_f32_e32 v17, v241, v17
	v_div_scale_f32 v179, s[40:41], v177, v177, v175
	v_div_scale_f32 v180, s[40:41], v178, v178, v176
	v_rcp_f32_e32 v181, v179
	v_rcp_f32_e32 v182, v180
	v_fma_f32 v183, -v179, v181, 1.0
	v_fma_f32 v184, -v180, v182, 1.0
	v_fmac_f32_e32 v181, v183, v181
	v_fmac_f32_e32 v182, v184, v182
	v_div_scale_f32 v183, vcc, v175, v177, v175
	v_mul_f32_e32 v185, v183, v181
	v_fma_f32 v187, -v179, v185, v183
	v_fmac_f32_e32 v185, v187, v181
	v_fma_f32 v179, -v179, v185, v183
	v_div_fmas_f32 v179, v179, v181, v185
	v_div_fixup_f32 v175, v179, v177, v175
	v_div_scale_f32 v184, vcc, v176, v178, v176
	v_mul_f32_e32 v186, v184, v182
	v_fma_f32 v187, -v180, v186, v184
	v_fmac_f32_e32 v186, v187, v182
	v_fma_f32 v180, -v180, v186, v184
	v_div_fmas_f32 v180, v180, v182, v186
	v_div_fixup_f32 v176, v180, v178, v176
	v_mul_f32_e32 v16, v175, v16
	v_mul_f32_e32 v17, v176, v17
	v_cvt_pk_bf16_f32 v158, v16, v17
	global_store_dword v168, v158, s[54:55]
	v_fmamk_f32 v140, v140, 0x3c000000, v212
	v_cmp_gt_f32_e32 vcc, s1, v140
	v_mul_f32_e32 v174, 0x4b800000, v140
	v_lshlrev_b32_e32 v175, 16, v243
	v_cndmask_b32_e32 v140, v140, v174, vcc
	v_rsq_f32_e32 v140, v140
	v_and_b32_e32 v176, 0xffff0000, v243
	v_mul_f32_e32 v174, 0x45800000, v140
	v_mul_f32_e32 v177, 0xbfb8aa3b, v175
	v_cndmask_b32_e32 v140, v140, v174, vcc
	v_exp_f32_e32 v177, v177
	v_mul_f32_e32 v178, 0xbfb8aa3b, v176
	v_exp_f32_e32 v178, v178
	v_mul_f32_e32 v18, v18, v140
	v_mul_f32_e32 v19, v19, v140
	v_add_f32_e32 v177, 1.0, v177
	v_add_f32_e32 v178, 1.0, v178
	v_mul_f32_e32 v18, v240, v18
	v_mul_f32_e32 v19, v241, v19
	v_div_scale_f32 v179, s[40:41], v177, v177, v175
	v_div_scale_f32 v180, s[40:41], v178, v178, v176
	v_rcp_f32_e32 v181, v179
	v_rcp_f32_e32 v182, v180
	v_fma_f32 v183, -v179, v181, 1.0
	v_fma_f32 v184, -v180, v182, 1.0
	v_fmac_f32_e32 v181, v183, v181
	v_fmac_f32_e32 v182, v184, v182
	v_div_scale_f32 v183, vcc, v175, v177, v175
	v_mul_f32_e32 v185, v183, v181
	v_fma_f32 v187, -v179, v185, v183
	v_fmac_f32_e32 v185, v187, v181
	v_fma_f32 v179, -v179, v185, v183
	v_div_fmas_f32 v179, v179, v181, v185
	v_div_fixup_f32 v175, v179, v177, v175
	v_div_scale_f32 v184, vcc, v176, v178, v176
	v_mul_f32_e32 v186, v184, v182
	v_fma_f32 v187, -v180, v186, v184
	v_fmac_f32_e32 v186, v187, v182
	v_fma_f32 v180, -v180, v186, v184
	v_div_fmas_f32 v180, v180, v182, v186
	v_div_fixup_f32 v176, v180, v178, v176
	v_mul_f32_e32 v18, v175, v18
	v_mul_f32_e32 v19, v176, v19
	v_cvt_pk_bf16_f32 v159, v18, v19
	global_store_dword v168, v159, s[54:55] offset:1024
	v_fmamk_f32 v142, v142, 0x3c000000, v212
	v_cmp_gt_f32_e32 vcc, s1, v142
	v_mul_f32_e32 v174, 0x4b800000, v142
	v_lshlrev_b32_e32 v175, 16, v244
	v_cndmask_b32_e32 v142, v142, v174, vcc
	v_rsq_f32_e32 v142, v142
	v_and_b32_e32 v176, 0xffff0000, v244
	v_mul_f32_e32 v174, 0x45800000, v142
	v_mul_f32_e32 v177, 0xbfb8aa3b, v175
	v_cndmask_b32_e32 v142, v142, v174, vcc
	v_exp_f32_e32 v177, v177
	v_mul_f32_e32 v178, 0xbfb8aa3b, v176
	v_exp_f32_e32 v178, v178
	v_mul_f32_e32 v20, v20, v142
	v_mul_f32_e32 v21, v21, v142
	v_add_f32_e32 v177, 1.0, v177
	v_add_f32_e32 v178, 1.0, v178
	v_mul_f32_e32 v20, v240, v20
	v_mul_f32_e32 v21, v241, v21
	v_div_scale_f32 v179, s[40:41], v177, v177, v175
	v_div_scale_f32 v180, s[40:41], v178, v178, v176
	v_rcp_f32_e32 v181, v179
	v_rcp_f32_e32 v182, v180
	v_fma_f32 v183, -v179, v181, 1.0
	v_fma_f32 v184, -v180, v182, 1.0
	v_fmac_f32_e32 v181, v183, v181
	v_fmac_f32_e32 v182, v184, v182
	v_div_scale_f32 v183, vcc, v175, v177, v175
	v_mul_f32_e32 v185, v183, v181
	v_fma_f32 v187, -v179, v185, v183
	v_fmac_f32_e32 v185, v187, v181
	v_fma_f32 v179, -v179, v185, v183
	v_div_fmas_f32 v179, v179, v181, v185
	v_div_fixup_f32 v175, v179, v177, v175
	v_div_scale_f32 v184, vcc, v176, v178, v176
	v_mul_f32_e32 v186, v184, v182
	v_fma_f32 v187, -v180, v186, v184
	v_fmac_f32_e32 v186, v187, v182
	v_fma_f32 v180, -v180, v186, v184
	v_div_fmas_f32 v180, v180, v182, v186
	v_div_fixup_f32 v176, v180, v178, v176
	v_mul_f32_e32 v20, v175, v20
	v_mul_f32_e32 v21, v176, v21
	v_cvt_pk_bf16_f32 v160, v20, v21
	global_store_dword v168, v160, s[54:55] offset:2048
	v_fmamk_f32 v144, v144, 0x3c000000, v212
	v_cmp_gt_f32_e32 vcc, s1, v144
	v_mul_f32_e32 v174, 0x4b800000, v144
	v_lshlrev_b32_e32 v175, 16, v245
	v_cndmask_b32_e32 v144, v144, v174, vcc
	v_rsq_f32_e32 v144, v144
	v_and_b32_e32 v176, 0xffff0000, v245
	v_mul_f32_e32 v174, 0x45800000, v144
	v_mul_f32_e32 v177, 0xbfb8aa3b, v175
	v_cndmask_b32_e32 v144, v144, v174, vcc
	v_exp_f32_e32 v177, v177
	v_mul_f32_e32 v178, 0xbfb8aa3b, v176
	v_exp_f32_e32 v178, v178
	v_mul_f32_e32 v22, v22, v144
	v_mul_f32_e32 v23, v23, v144
	v_add_f32_e32 v177, 1.0, v177
	v_add_f32_e32 v178, 1.0, v178
	v_mul_f32_e32 v22, v240, v22
	v_mul_f32_e32 v23, v241, v23
	v_div_scale_f32 v179, s[40:41], v177, v177, v175
	v_div_scale_f32 v180, s[40:41], v178, v178, v176
	v_rcp_f32_e32 v181, v179
	v_rcp_f32_e32 v182, v180
	v_fma_f32 v183, -v179, v181, 1.0
	v_fma_f32 v184, -v180, v182, 1.0
	v_fmac_f32_e32 v181, v183, v181
; __device__ __forceinline__ unsigned cvt_pk_bf16(float lo, float hi) { unsigned r; asm("v_cvt_pk_bf16_f32 %0, %1, %2" : "=v"(r) : "v"(lo), "v"(hi)); return r; }
; __device__ __forceinline__ float bf_lo(unsigned w) { return __uint_as_float(w << 16); }
; __device__ __forceinline__ float bf_hi(unsigned w) { return __uint_as_float(w & 0xffff0000u); }
; __device__ void gla_pass2(const Params& p, int l, const bf16_t* proj, bf16_t* ycat, LAS unsigned char* lds) {
;     ...
;             for (int j = 0; j < 8; ++j) { const int t = seg * SEGLEN + wv * 32 + j0 + j;
;                 const float o0 = of[j][0] + ob[j][0], o1 = of[j][1] + ob[j][1];
;                 const float ss = wave_sum(o0 * o0 + o1 * o1);
;                 const float rs = rsqrtf(ss * (1.0f / 128.0f) + 1e-6f);
;                 const float r0 = bf_lo(rw[j]), r1 = bf_hi(rw[j]);
;                 const float y0 = o0 * rs * gg[0] * (r0 / (1.0f + __expf(-r0))), y1 = o1 * rs * gg[1] * (r1 / (1.0f + __expf(-r1)));
;                 *(unsigned*)(ycat + (size_t)2 * SEQ * 512 + (size_t)t * 512 + h * 128 + lane * 2) = cvt_pk_bf16(y0, y1); } }
	v_fmac_f32_e32 v182, v184, v182
	v_div_scale_f32 v183, vcc, v175, v177, v175
	v_mul_f32_e32 v185, v183, v181
	v_fma_f32 v187, -v179, v185, v183
	v_fmac_f32_e32 v185, v187, v181
	v_fma_f32 v179, -v179, v185, v183
	v_div_fmas_f32 v179, v179, v181, v185
	v_div_fixup_f32 v175, v179, v177, v175
	v_div_scale_f32 v184, vcc, v176, v178, v176
	v_mul_f32_e32 v186, v184, v182
	v_fma_f32 v187, -v180, v186, v184
	v_fmac_f32_e32 v186, v187, v182
	v_fma_f32 v180, -v180, v186, v184
	v_div_fmas_f32 v180, v180, v182, v186
	v_div_fixup_f32 v176, v180, v178, v176
	v_mul_f32_e32 v22, v175, v22
	v_mul_f32_e32 v23, v176, v23
	v_cvt_pk_bf16_f32 v161, v22, v23
	global_store_dword v168, v161, s[54:55] offset:3072
	v_fmamk_f32 v146, v146, 0x3c000000, v212
	v_cmp_gt_f32_e32 vcc, s1, v146
	v_mul_f32_e32 v174, 0x4b800000, v146
	v_lshlrev_b32_e32 v175, 16, v246
	v_cndmask_b32_e32 v146, v146, v174, vcc
	v_rsq_f32_e32 v146, v146
	v_and_b32_e32 v176, 0xffff0000, v246
	v_mul_f32_e32 v174, 0x45800000, v146
	v_mul_f32_e32 v177, 0xbfb8aa3b, v175
	v_cndmask_b32_e32 v146, v146, v174, vcc
	v_exp_f32_e32 v177, v177
	v_mul_f32_e32 v178, 0xbfb8aa3b, v176
	v_exp_f32_e32 v178, v178
	v_mul_f32_e32 v24, v24, v146
	v_mul_f32_e32 v25, v25, v146
	v_add_f32_e32 v177, 1.0, v177
	v_add_f32_e32 v178, 1.0, v178
	v_mul_f32_e32 v24, v240, v24
	v_mul_f32_e32 v25, v241, v25
	v_div_scale_f32 v179, s[40:41], v177, v177, v175
	v_div_scale_f32 v180, s[40:41], v178, v178, v176
	v_rcp_f32_e32 v181, v179
	v_rcp_f32_e32 v182, v180
	v_fma_f32 v183, -v179, v181, 1.0
	v_fma_f32 v184, -v180, v182, 1.0
	v_fmac_f32_e32 v181, v183, v181
	v_fmac_f32_e32 v182, v184, v182
	v_div_scale_f32 v183, vcc, v175, v177, v175
	v_mul_f32_e32 v185, v183, v181
	v_fma_f32 v187, -v179, v185, v183
	v_fmac_f32_e32 v185, v187, v181
	v_fma_f32 v179, -v179, v185, v183
	v_div_fmas_f32 v179, v179, v181, v185
	v_div_fixup_f32 v175, v179, v177, v175
	v_div_scale_f32 v184, vcc, v176, v178, v176
	v_mul_f32_e32 v186, v184, v182
	v_fma_f32 v187, -v180, v186, v184
	v_fmac_f32_e32 v186, v187, v182
	v_fma_f32 v180, -v180, v186, v184
	v_div_fmas_f32 v180, v180, v182, v186
	v_div_fixup_f32 v176, v180, v178, v176
	v_mul_f32_e32 v24, v175, v24
	v_mul_f32_e32 v25, v176, v25
	v_cvt_pk_bf16_f32 v162, v24, v25
	global_store_dword v168, v162, s[56:57]
	v_fmamk_f32 v148, v148, 0x3c000000, v212
	v_cmp_gt_f32_e32 vcc, s1, v148
	v_mul_f32_e32 v174, 0x4b800000, v148
	v_lshlrev_b32_e32 v175, 16, v247
	v_cndmask_b32_e32 v148, v148, v174, vcc
	v_rsq_f32_e32 v148, v148
	v_and_b32_e32 v176, 0xffff0000, v247
	v_mul_f32_e32 v174, 0x45800000, v148
	v_mul_f32_e32 v177, 0xbfb8aa3b, v175
	v_cndmask_b32_e32 v148, v148, v174, vcc
	v_exp_f32_e32 v177, v177
	v_mul_f32_e32 v178, 0xbfb8aa3b, v176
	v_exp_f32_e32 v178, v178
	v_mul_f32_e32 v26, v26, v148
	v_mul_f32_e32 v27, v27, v148
	v_add_f32_e32 v177, 1.0, v177
	v_add_f32_e32 v178, 1.0, v178
	v_mul_f32_e32 v26, v240, v26
	v_mul_f32_e32 v27, v241, v27
	v_div_scale_f32 v179, s[40:41], v177, v177, v175
	v_div_scale_f32 v180, s[40:41], v178, v178, v176
	v_rcp_f32_e32 v181, v179
	v_rcp_f32_e32 v182, v180
	v_fma_f32 v183, -v179, v181, 1.0
	v_fma_f32 v184, -v180, v182, 1.0
	v_fmac_f32_e32 v181, v183, v181
	v_fmac_f32_e32 v182, v184, v182
	v_div_scale_f32 v183, vcc, v175, v177, v175
	v_mul_f32_e32 v185, v183, v181
	v_fma_f32 v187, -v179, v185, v183
	v_fmac_f32_e32 v185, v187, v181
	v_fma_f32 v179, -v179, v185, v183
	v_div_fmas_f32 v179, v179, v181, v185
	v_div_fixup_f32 v175, v179, v177, v175
	v_div_scale_f32 v184, vcc, v176, v178, v176
	v_mul_f32_e32 v186, v184, v182
	v_fma_f32 v187, -v180, v186, v184
; __device__ __forceinline__ unsigned cvt_pk_bf16(float lo, float hi) { unsigned r; asm("v_cvt_pk_bf16_f32 %0, %1, %2" : "=v"(r) : "v"(lo), "v"(hi)); return r; }
; __device__ __forceinline__ float bf_lo(unsigned w) { return __uint_as_float(w << 16); }
; __device__ __forceinline__ float bf_hi(unsigned w) { return __uint_as_float(w & 0xffff0000u); }
; __device__ void gla_pass2(const Params& p, int l, const bf16_t* proj, bf16_t* ycat, LAS unsigned char* lds) {
;     ...
;             for (int j = 0; j < 8; ++j) { const int t = seg * SEGLEN + wv * 32 + j0 + j;
;                 const float o0 = of[j][0] + ob[j][0], o1 = of[j][1] + ob[j][1];
;                 const float ss = wave_sum(o0 * o0 + o1 * o1);
;                 const float rs = rsqrtf(ss * (1.0f / 128.0f) + 1e-6f);
;                 const float r0 = bf_lo(rw[j]), r1 = bf_hi(rw[j]);
;                 const float y0 = o0 * rs * gg[0] * (r0 / (1.0f + __expf(-r0))), y1 = o1 * rs * gg[1] * (r1 / (1.0f + __expf(-r1)));
;                 *(unsigned*)(ycat + (size_t)2 * SEQ * 512 + (size_t)t * 512 + h * 128 + lane * 2) = cvt_pk_bf16(y0, y1); } }
	v_fmac_f32_e32 v186, v187, v182
	v_fma_f32 v180, -v180, v186, v184
	v_div_fmas_f32 v180, v180, v182, v186
	v_div_fixup_f32 v176, v180, v178, v176
	v_mul_f32_e32 v26, v175, v26
	v_mul_f32_e32 v27, v176, v27
	v_cvt_pk_bf16_f32 v163, v26, v27
	global_store_dword v168, v163, s[56:57] offset:1024
	v_fmamk_f32 v150, v150, 0x3c000000, v212
	v_cmp_gt_f32_e32 vcc, s1, v150
	v_mul_f32_e32 v174, 0x4b800000, v150
	v_lshlrev_b32_e32 v175, 16, v248
	v_cndmask_b32_e32 v150, v150, v174, vcc
	v_rsq_f32_e32 v150, v150
	v_and_b32_e32 v176, 0xffff0000, v248
	v_mul_f32_e32 v174, 0x45800000, v150
	v_mul_f32_e32 v177, 0xbfb8aa3b, v175
	v_cndmask_b32_e32 v150, v150, v174, vcc
	v_exp_f32_e32 v177, v177
	v_mul_f32_e32 v178, 0xbfb8aa3b, v176
	v_exp_f32_e32 v178, v178
	v_mul_f32_e32 v28, v28, v150
	v_mul_f32_e32 v29, v29, v150
	v_add_f32_e32 v177, 1.0, v177
	v_add_f32_e32 v178, 1.0, v178
	v_mul_f32_e32 v28, v240, v28
	v_mul_f32_e32 v29, v241, v29
	v_div_scale_f32 v179, s[40:41], v177, v177, v175
	v_div_scale_f32 v180, s[40:41], v178, v178, v176
	v_rcp_f32_e32 v181, v179
	v_rcp_f32_e32 v182, v180
	v_fma_f32 v183, -v179, v181, 1.0
	v_fma_f32 v184, -v180, v182, 1.0
	v_fmac_f32_e32 v181, v183, v181
	v_fmac_f32_e32 v182, v184, v182
	v_div_scale_f32 v183, vcc, v175, v177, v175
	v_mul_f32_e32 v185, v183, v181
	v_fma_f32 v187, -v179, v185, v183
	v_fmac_f32_e32 v185, v187, v181
	v_fma_f32 v179, -v179, v185, v183
	v_div_fmas_f32 v179, v179, v181, v185
	v_div_fixup_f32 v175, v179, v177, v175
	v_div_scale_f32 v184, vcc, v176, v178, v176
	v_mul_f32_e32 v186, v184, v182
	v_fma_f32 v187, -v180, v186, v184
	v_fmac_f32_e32 v186, v187, v182
	v_fma_f32 v180, -v180, v186, v184
	v_div_fmas_f32 v180, v180, v182, v186
	v_div_fixup_f32 v176, v180, v178, v176
	v_mul_f32_e32 v28, v175, v28
	v_mul_f32_e32 v29, v176, v29
	v_cvt_pk_bf16_f32 v164, v28, v29
	global_store_dword v168, v164, s[56:57] offset:2048
	v_fmamk_f32 v152, v152, 0x3c000000, v212
	v_cmp_gt_f32_e32 vcc, s1, v152
	v_mul_f32_e32 v174, 0x4b800000, v152
	v_lshlrev_b32_e32 v175, 16, v249
	v_cndmask_b32_e32 v152, v152, v174, vcc
	v_rsq_f32_e32 v152, v152
	v_and_b32_e32 v176, 0xffff0000, v249
	v_mul_f32_e32 v174, 0x45800000, v152
	v_mul_f32_e32 v177, 0xbfb8aa3b, v175
	v_cndmask_b32_e32 v152, v152, v174, vcc
	v_exp_f32_e32 v177, v177
	v_mul_f32_e32 v178, 0xbfb8aa3b, v176
	v_exp_f32_e32 v178, v178
	v_mul_f32_e32 v30, v30, v152
	v_mul_f32_e32 v31, v31, v152
	v_add_f32_e32 v177, 1.0, v177
	v_add_f32_e32 v178, 1.0, v178
	v_mul_f32_e32 v30, v240, v30
	v_mul_f32_e32 v31, v241, v31
	v_div_scale_f32 v179, s[40:41], v177, v177, v175
	v_div_scale_f32 v180, s[40:41], v178, v178, v176
	v_rcp_f32_e32 v181, v179
	v_rcp_f32_e32 v182, v180
	v_fma_f32 v183, -v179, v181, 1.0
	v_fma_f32 v184, -v180, v182, 1.0
	v_fmac_f32_e32 v181, v183, v181
	v_fmac_f32_e32 v182, v184, v182
	v_div_scale_f32 v183, vcc, v175, v177, v175
	v_mul_f32_e32 v185, v183, v181
	v_fma_f32 v187, -v179, v185, v183
	v_fmac_f32_e32 v185, v187, v181
	v_fma_f32 v179, -v179, v185, v183
	v_div_fmas_f32 v179, v179, v181, v185
	v_div_fixup_f32 v175, v179, v177, v175
	v_div_scale_f32 v184, vcc, v176, v178, v176
	v_mul_f32_e32 v186, v184, v182
	v_fma_f32 v187, -v180, v186, v184
	v_fmac_f32_e32 v186, v187, v182
	v_fma_f32 v180, -v180, v186, v184
	v_div_fmas_f32 v180, v180, v182, v186
	v_div_fixup_f32 v176, v180, v178, v176
	v_mul_f32_e32 v30, v175, v30
	v_mul_f32_e32 v31, v176, v31
	v_cvt_pk_bf16_f32 v165, v30, v31
	global_store_dword v168, v165, s[56:57] offset:3072
	s_cmp_lg_u32 s51, 4
	s_cbranch_scc0 .LBB0_433
	s_branch .LBB0_436

; #define LAS __attribute__((address_space(3)))
; __device__ __forceinline__ float bf_lo(unsigned w) { return __uint_as_float(w << 16); }
; template <bool OUT>
; __device__ __forceinline__ void gla_chunks(const Params& p, int l, const bf16_t* proj, LAS unsigned char* lds, int seg, int h, int dir, f32x4 (&Sacc)[4], float* outbuf, float& alog) {
;     ...
;         const int t0 = seg * SEGLEN + (dir ? 3 - c : c) * 64;
;         float bq[8], qv[8], kv[8];
;         { u32x4 L0[8], L1[8]; bf16_t kr[8], qr[8];
; #pragma unroll
;           for (int j = 0; j < 8; ++j) { const int i = tb * 8 + j, t = dir ? t0 + 63 - i : t0 + i;
;               const u32x4* lr = (const u32x4*)(proj + (size_t)t * NP + GLR + dir * 16); L0[j] = lr[0]; L1[j] = lr[1];
;               kr[j] = proj[(size_t)t * NP + GK + h * 64 + d]; qr[j] = OUT ? proj[(size_t)t * NP + GQ + h * 64 + d] : (bf16_t)0; }
;           __builtin_amdgcn_sched_barrier(0);
;           float run = 0.f;
; #pragma unroll
;           for (int j = 0; j < 8; ++j) { const u32x4 l0 = L0[j], l1 = L1[j]; float z = bias;
; #pragma unroll
;               for (int e = 0; e < 4; ++e) { z += bf_lo(l0[e]) * w[e * 2] + bf_hi(l0[e]) * w[e * 2 + 1]; z += bf_lo(l1[e]) * w[8 + e * 2] + bf_hi(l1[e]) * w[8 + e * 2 + 1]; }
;               const float ls = fminf(z, 0.f) - __logf(1.0f + __expf(-fabsf(z)));
;               run += ls * (1.0f / 16.0f); bq[j] = run;
;               kv[j] = bf2f(kr[j]);
;               if (OUT) qv[j] = bf2f(qr[j]) * 0.125f; }
;           PART[tb * 64 + d] = run; }
;         { const int pr = tid >> 4, part = tid & 15; const int i0 = 2 * pr, ta = dir ? t0 + 63 - i0 : t0 + i0, tbb = dir ? ta - 1 : ta + 1;
;           const u32x4 a = *(const u32x4*)(proj + (size_t)ta * NP + GV + h * 128 + part * 8), b = *(const u32x4*)(proj + (size_t)tbb * NP + GV + h * 128 + part * 8);
; #pragma unroll
;           for (int e = 0; e < 4; ++e) {
;               *(LAS unsigned*)(VT + (part * 8 + 2 * e) * GP + i0) = (a[e] & 0xffffu) | (b[e] << 16);
;               *(LAS unsigned*)(VT + (part * 8 + 2 * e + 1) * GP + i0) = (a[e] >> 16) | (b[e] & 0xffff0000u); } }
;         __syncthreads();
;         { float off = 0.f, tot = 0.f;
; #pragma unroll
;           for (int q = 0; q < 8; ++q) { const float v = PART[q * 64 + d]; tot += v; if (q < tb) off += v; }
;           if (tb == 0) { EBL[d] = __expf(tot); alog += tot; }
.LBB0_436:
	s_and_b64 s[40:41], s[42:43], exec
	s_cselect_b32 s40, s51, s64
	s_lshl_b32 s52, s40, 6
	s_add_i32 s52, s52, s68
	s_or_b32 s53, s52, 63
	s_and_b64 s[40:41], s[42:43], exec
	s_cbranch_scc1 .Lp2_nopf
	v_and_b32_e32 v43, 63, v83
	s_lshl_b32 s40, s66, 2
	v_lshlrev_b32_e32 v44, 2, v43
	v_add_u32_e32 v44, s40, v44
	v_mul_u32_u24_e32 v45, 0x1c000, v90
	v_add_u32_e32 v44, v45, v44
	v_lshlrev_b32_e32 v45, 3, v43
	v_readlane_b32 s56, v255, 55
	v_readlane_b32 s57, v255, 56
	s_add_u32 s56, s56, s67
	s_addc_u32 s57, s57, 0
	s_nop 2
	global_load_dwordx2 v[240:241], v45, s[56:57]
	s_mul_i32 s40, s52, 0x3800
	s_add_u32 s40, s40, 0x20604200
	s_add_u32 s40, s86, s40
	s_addc_u32 s41, s87, 0
	global_load_dword v242, v44, s[40:41]
	s_add_u32 s40, s40, 0x3800
	s_addc_u32 s41, s41, 0
	global_load_dword v243, v44, s[40:41]
	s_add_u32 s40, s40, 0x3800
	s_addc_u32 s41, s41, 0
	global_load_dword v244, v44, s[40:41]
	s_add_u32 s40, s40, 0x3800
	s_addc_u32 s41, s41, 0
	global_load_dword v245, v44, s[40:41]
	s_add_u32 s40, s40, 0x3800
	s_addc_u32 s41, s41, 0
	global_load_dword v246, v44, s[40:41]
	s_add_u32 s40, s40, 0x3800
	s_addc_u32 s41, s41, 0
	global_load_dword v247, v44, s[40:41]
	s_add_u32 s40, s40, 0x3800
	s_addc_u32 s41, s41, 0
	global_load_dword v248, v44, s[40:41]
	s_add_u32 s40, s40, 0x3800
	s_addc_u32 s41, s41, 0
	global_load_dword v249, v44, s[40:41]
.Lp2_nopf:
	s_sub_i32 s54, s53, s33
	s_add_i32 s55, s52, s33
	s_and_b64 s[40:41], s[42:43], exec
	s_cselect_b32 s40, s55, s54
	s_cselect_b32 s41, 1, -1
	s_lshl_b32 s41, s41, 11
	s_lshl_b32 s54, s40, 11
	s_lshl_b32 s55, s50, 5
	s_add_i32 s54, s54, s55
	s_lshl_b32 s55, s66, 2
	s_add_i32 s54, s54, s55
	s_add_u32 s56, s94, 0x11000000
	s_addc_u32 s57, s95, 0
	v_add_u32_e32 v164, s54, v110
	global_load_dword v156, v164, s[56:57]
	v_add_u32_e32 v165, s41, v164
	global_load_dword v157, v165, s[56:57]
	v_add_u32_e32 v164, s41, v165
	global_load_dword v158, v164, s[56:57]
	v_add_u32_e32 v165, s41, v164
	global_load_dword v159, v165, s[56:57]
	v_add_u32_e32 v164, s41, v165
	global_load_dword v160, v164, s[56:57]
	v_add_u32_e32 v165, s41, v164
	global_load_dword v161, v165, s[56:57]
	v_add_u32_e32 v164, s41, v165
	global_load_dword v162, v164, s[56:57]
	v_add_u32_e32 v165, s41, v164
	global_load_dword v163, v165, s[56:57]
	s_mul_hi_i32 s41, s40, 0x3800
	s_mulk_i32 s40, 0x3800
	s_add_u32 s56, s94, s40
	s_addc_u32 s57, s95, s41
	s_lshl_b32 s40, s66, 1
	s_add_u32 s54, s56, s40
	s_addc_u32 s55, s57, 0
	s_add_u32 s54, s54, 0x2a00
	s_addc_u32 s55, s55, 0
	s_movk_i32 s40, 0x3800
	s_and_b64 s[56:57], s[42:43], exec
	s_cselect_b32 s40, s40, 0xffffc800
	s_cselect_b32 s41, 0, -1
	global_load_ushort v138, v188, s[54:55] offset:512
	global_load_ushort v139, v188, s[54:55]
	s_add_u32 s54, s54, s40
	s_addc_u32 s55, s55, s41
	global_load_ushort v140, v188, s[54:55] offset:512
	global_load_ushort v141, v188, s[54:55]
	s_add_u32 s54, s54, s40
	s_addc_u32 s55, s55, s41
	global_load_ushort v142, v188, s[54:55] offset:512
	global_load_ushort v143, v188, s[54:55]
	s_add_u32 s54, s54, s40
	s_addc_u32 s55, s55, s41
	global_load_ushort v144, v188, s[54:55] offset:512
	global_load_ushort v145, v188, s[54:55]
	s_add_u32 s54, s54, s40
	s_addc_u32 s55, s55, s41
	global_load_ushort v146, v188, s[54:55] offset:512
	global_load_ushort v147, v188, s[54:55]
	s_add_u32 s54, s54, s40
	s_addc_u32 s55, s55, s41
	global_load_ushort v148, v188, s[54:55] offset:512
	global_load_ushort v149, v188, s[54:55]
	s_add_u32 s54, s54, s40
	s_addc_u32 s55, s55, s41
	global_load_ushort v150, v188, s[54:55] offset:512
	global_load_ushort v151, v188, s[54:55]
	s_add_u32 s54, s54, s40
	s_addc_u32 s55, s55, s41
	global_load_ushort v152, v188, s[54:55] offset:512
	global_load_ushort v153, v188, s[54:55]
	s_lshl_b32 s90, s72, 1
	v_mov_b32_e32 v89, v189
	v_sub_u32_e32 v24, s53, v109
	v_add_u32_e32 v25, s52, v109
	v_cndmask_b32_e64 v26, v24, v25, s[42:43]
	v_mov_b64_e32 v[24:25], s[94:95]
	v_add_u32_e32 v28, s76, v26
	v_mad_i64_i32 v[26:27], s[40:41], v26, s63, v[24:25]
	v_lshl_add_u64 v[26:27], v[26:27], 0, s[90:91]
	v_lshl_add_u64 v[26:27], v[26:27], 0, v[88:89]
	v_mad_i64_i32 v[24:25], s[40:41], v28, s63, v[24:25]
	v_add_co_u32_e32 v26, vcc, s92, v26
	v_lshl_add_u64 v[24:25], v[24:25], 0, s[90:91]
	s_nop 0
	v_addc_co_u32_e32 v27, vcc, 0, v27, vcc
	v_lshl_add_u64 v[24:25], v[24:25], 0, v[88:89]
	s_nop 0
	v_add_co_u32_e32 v24, vcc, s92, v24
	s_nop 0
	s_nop 0
	v_addc_co_u32_e32 v25, vcc, 0, v25, vcc
	global_load_dwordx4 v[28:31], v[26:27], off offset:3584
	global_load_dwordx4 v[34:37], v[24:25], off offset:3584
	s_nop 0
	s_waitcnt vmcnt(0)
	v_mov_b32_e32 v64, v156
	v_mov_b32_e32 v56, v157
	v_mov_b32_e32 v40, v158
	v_mov_b32_e32 v41, v159
	v_mov_b32_e32 v32, v160
	v_mov_b32_e32 v24, v161
	v_mov_b32_e32 v25, v162
	v_mov_b32_e32 v26, v163
	v_and_b32_e32 v16, 0xffff, v28
	v_lshrrev_b32_e32 v17, 16, v28
	v_lshl_or_b32 v16, v34, 16, v16
	v_and_or_b32 v17, v34, s0, v17
	v_add_u32_e32 v18, 0x6c00, v112
	ds_write2_b32 v18, v16, v17 offset1:36
	v_and_b32_e32 v16, 0xffff, v29
	v_lshrrev_b32_e32 v17, 16, v29
	v_lshl_or_b32 v16, v35, 16, v16
	v_and_or_b32 v17, v35, s0, v17
	ds_write2_b32 v18, v16, v17 offset0:72 offset1:108
	v_and_b32_e32 v16, 0xffff, v30
	v_lshrrev_b32_e32 v17, 16, v30
	v_lshl_or_b32 v16, v36, 16, v16
	v_and_or_b32 v17, v36, s0, v17
	ds_write2_b32 v18, v16, v17 offset0:144 offset1:180
	v_and_b32_e32 v16, 0xffff, v31
	v_lshrrev_b32_e32 v17, 16, v31
	v_lshl_or_b32 v16, v37, 16, v16
	v_and_or_b32 v17, v37, s0, v17
	ds_write_b32 v108, v26 offset:55552
	ds_write2_b32 v18, v16, v17 offset0:216 offset1:252
	s_waitcnt lgkmcnt(0)
	s_barrier
	ds_read2st64_b32 v[22:23], v110 offset0:217 offset1:218
	ds_read2st64_b32 v[20:21], v110 offset0:219 offset1:220
	ds_read2st64_b32 v[18:19], v110 offset0:221 offset1:222
	ds_read2st64_b32 v[16:17], v110 offset0:223 offset1:224
	s_andn2_b64 vcc, exec, s[80:81]
	s_waitcnt lgkmcnt(3)
	v_add_f32_e32 v28, 0, v22
	v_add_f32_e32 v22, v28, v23
	s_waitcnt lgkmcnt(2)
	v_add_f32_e32 v22, v22, v20
	v_add_f32_e32 v22, v22, v21
	s_waitcnt lgkmcnt(1)
	v_add_f32_e32 v22, v22, v18
	v_add_f32_e32 v22, v22, v19
	s_waitcnt lgkmcnt(0)
	v_add_f32_e32 v22, v22, v16
	v_add_f32_e32 v27, v22, v17
	s_cbranch_vccnz .LBB0_438
	v_mul_f32_e32 v22, 0x3fb8aa3b, v27
	v_exp_f32_e32 v22, v22
	ds_write_b32 v110, v22 offset:55296
